# scan loader writes v pairs as (vA,vB,vA*kr,vB*kr) so the step loop needs no v_swap
# speedup vs baseline: 1.0276x; 1.0016x over previous
; #define INP(a, i) inp_(a, i)
; #define SC_LOAD2(c) do { SC_LOAD(c, tl0, pr, pk, pv, pa, pd); SC_LOAD(c, tl0 + 16, pr2, pk2_, pv2, pa2, pd2); } while (0)
; #define SC_STORE2(bi) do { SC_STORE(bi, tl0, pr, pk, pv, pa, pd); SC_STORE(bi, tl0 + 16, pr2, pk2_, pv2, pa2, pd2); } while (0)
; DI void scan_phase(unsigned char* lds, const Ctx& a, const Op& d, const int variant) {
;     ...
;         const f32x4 kk4 = *(const f32x4*)(INP(a, 18) + ia * DM + chan), ka4 = *(const f32x4*)(INP(a, 19) + ia * DM + chan);
;         const size_t rowbase = (size_t)b * SEQ;
;         u32x2 pr, pk, pv, pa; f32x4 pd;
;     ...
;         const bool is_loader = wave >= 4;
;         const int ltid = tid & 255, tl0 = ltid >> 4;
;         u32x2 pr2, pk2_, pv2, pa2; f32x4 pd2;
;         const int rA = (wave & 3) * 8 + 2 * ii;
;         f32x2 SA01 = {0.f, 0.f}, SA23 = {0.f, 0.f}, SB01 = {0.f, 0.f}, SB23 = {0.f, 0.f};
;     ...
;         constexpr int NCH = SEQ / SC_T;
;         float* cv_scr = (float*)(lds + 2 * SC_BUF + (wave & 3) * 8448);
;         const int cv_total = (ia == 0) ? 32768 : 16384, cv_mask = (ia == 0) ? 3 : 7;
;         int cv_item = a.bid * 4 + (wave & 3), cv_pend = -1;
;         f32x4 cvr[8];
;     ...
;         __syncthreads();
;         if (is_loader) { SC_LOAD2(0); SC_STORE2(0); SC_LOAD2(1); }
.LBB0_444:
	s_waitcnt vmcnt(0)
	v_mov_b64_e32 v[32:33], s[58:59]
	flat_load_dwordx4 v[34:37], v[32:33] offset:144
	s_lshl_b32 s6, s44, 5
	s_and_b32 s45, s6, 0x7c0
	v_readlane_b32 s6, v231, 20
	v_readlane_b32 s7, v231, 21
	s_lshl_b64 s[6:7], s[6:7], 2
	v_or_b32_e32 v172, s45, v115
	v_lshlrev_b32_e32 v96, 2, v172
	s_waitcnt vmcnt(0) lgkmcnt(0)
	v_readfirstlane_b32 s10, v34
	v_readfirstlane_b32 s11, v35
	s_add_u32 s10, s10, s6
	s_addc_u32 s11, s11, s7
	v_lshl_add_u64 v[32:33], s[10:11], 0, v[96:97]
	v_readfirstlane_b32 s10, v36
	v_readfirstlane_b32 s11, v37
	s_add_u32 s6, s10, s6
	s_addc_u32 s7, s11, s7
	v_lshl_add_u64 v[36:37], s[6:7], 0, v[96:97]
	flat_load_dwordx4 v[32:35], v[32:33]
	s_nop 0
	flat_load_dwordx4 v[36:39], v[36:37]
	s_waitcnt lgkmcnt(0)
	s_barrier
	s_and_saveexec_b64 s[6:7], s[8:9]
	s_xor_b64 s[6:7], exec, s[6:7]
	s_or_saveexec_b64 s[28:29], s[6:7]
	s_ashr_i32 s6, s44, 6
	s_ashr_i32 s7, s6, 31
	s_and_b32 s30, s44, 1
	s_lshl_b64 s[26:27], s[6:7], 12
	s_xor_b64 exec, exec, s[28:29]
	s_cbranch_execz .LBB0_450
	v_mov_b32_e32 v41, s27
	v_or_b32_e32 v40, s26, v114
	v_lshlrev_b64 v[40:41], 11, v[40:41]
	v_or_b32_e32 v40, v40, v172
	v_lshlrev_b64 v[42:43], 1, v[40:41]
	v_lshl_add_u64 v[44:45], s[18:19], 0, v[42:43]
	flat_load_dwordx2 v[62:63], v[44:45]
	v_lshl_add_u64 v[44:45], s[20:21], 0, v[42:43]
	flat_load_dwordx2 v[58:59], v[44:45]
	v_lshl_add_u64 v[44:45], s[24:25], 0, v[42:43]
	v_lshl_add_u64 v[42:43], s[22:23], 0, v[42:43]
	flat_load_dwordx2 v[64:65], v[42:43]
	v_lshl_add_u64 v[40:41], v[40:41], 2, s[12:13]
	flat_load_dwordx2 v[54:55], v[44:45]
	s_mov_b32 s6, 0xf800000
	flat_load_dwordx4 v[44:47], v[40:41]
	v_mov_b32_e32 v41, s27
	v_or_b32_e32 v40, s26, v116
	v_lshlrev_b64 v[40:41], 11, v[40:41]
	v_or_b32_e32 v40, v40, v172
	v_lshlrev_b64 v[42:43], 1, v[40:41]
	v_lshl_add_u64 v[48:49], s[18:19], 0, v[42:43]
	flat_load_dwordx2 v[50:51], v[48:49]
	v_lshl_add_u64 v[48:49], s[20:21], 0, v[42:43]
	flat_load_dwordx2 v[56:57], v[48:49]
	v_lshl_add_u64 v[48:49], s[24:25], 0, v[42:43]
	v_lshl_add_u64 v[42:43], s[22:23], 0, v[42:43]
	v_lshl_add_u64 v[40:41], v[40:41], 2, s[12:13]
	flat_load_dwordx2 v[48:49], v[48:49]
	v_add_u32_e32 v68, 0, v117
	flat_load_dwordx2 v[52:53], v[42:43]
	s_waitcnt vmcnt(0) lgkmcnt(0)
	v_lshlrev_b32_e32 v70, 16, v58
	flat_load_dwordx4 v[40:43], v[40:41]
	v_and_b32_e32 v71, 0xffff0000, v58
	v_lshlrev_b32_e32 v66, 16, v59
	v_and_b32_e32 v67, 0xffff0000, v59
	v_pk_mul_f32 v[60:61], v[32:33], v[70:71]
	v_pk_mul_f32 v[72:73], v[34:35], v[66:67]
	v_mov_b32_e32 v74, v61
	v_mov_b32_e32 v75, v73
	v_mov_b32_e32 v58, v60
	v_mov_b32_e32 v59, v72
	v_pk_mul_f32 v[74:75], v[74:75], v[74:75]
	ds_write_b128 v68, v[44:47]
	v_pk_fma_f32 v[58:59], v[58:59], v[58:59], v[74:75]
	s_nop 0
	v_add_f32_e32 v58, v58, v59
	s_nop 1
	v_add_f32_dpp v58, v58, v58 quad_perm:[1,0,3,2] row_mask:0xf bank_mask:0xf bound_ctrl:1
	s_nop 1
	v_add_f32_dpp v58, v58, v58 quad_perm:[2,3,0,1] row_mask:0xf bank_mask:0xf bound_ctrl:1
	s_nop 1
	v_add_f32_dpp v58, v58, v58 row_half_mirror row_mask:0xf bank_mask:0xf bound_ctrl:1
	s_nop 1
	v_add_f32_dpp v58, v58, v58 row_mirror row_mask:0xf bank_mask:0xf bound_ctrl:1
	v_cmp_gt_f32_e32 vcc, s6, v58
	v_mul_f32_e32 v59, 0x4f800000, v58
	s_nop 0
	v_cndmask_b32_e32 v58, v58, v59, vcc
	v_sqrt_f32_e32 v59, v58
	s_nop 0
	v_add_u32_e32 v69, -1, v59
	v_fma_f32 v74, -v69, v59, v58
	v_cmp_ge_f32_e64 s[6:7], 0, v74
	v_add_u32_e32 v74, 1, v59
	s_nop 0
	v_cndmask_b32_e64 v69, v59, v69, s[6:7]
	v_fma_f32 v59, -v74, v59, v58
	v_cmp_lt_f32_e64 s[6:7], 0, v59
	s_nop 1
	v_cndmask_b32_e64 v59, v69, v74, s[6:7]
	v_mul_f32_e32 v69, 0x37800000, v59
	v_cndmask_b32_e32 v59, v59, v69, vcc
	v_cmp_class_f32_e32 vcc, v58, v181
	s_nop 1
	v_cndmask_b32_e32 v58, v59, v58, vcc
	v_max_f32_e32 v58, 0x2b8cbccc, v58
	v_div_scale_f32 v59, s[6:7], v58, v58, 1.0
	v_rcp_f32_e32 v69, v59
	v_cmp_eq_u32_e64 s[6:7], s30, v119
	v_fma_f32 v74, -v59, v69, 1.0
	v_fmac_f32_e32 v69, v74, v69
	v_div_scale_f32 v74, vcc, 1.0, v58, 1.0
	v_mul_f32_e32 v75, v74, v69
	v_fma_f32 v76, -v59, v75, v74
	v_fmac_f32_e32 v75, v76, v69
	v_fma_f32 v59, -v59, v75, v74
	v_div_fmas_f32 v59, v59, v69, v75
	v_div_fixup_f32 v74, v59, v58, 1.0
	v_pk_mul_f32 v[58:59], v[60:61], v[74:75] op_sel_hi:[1,0]
	v_pk_mul_f32 v[60:61], v[72:73], v[74:75] op_sel_hi:[1,0]
	v_lshlrev_b32_e32 v72, 16, v64
	v_and_b32_e32 v73, 0xffff0000, v64
	v_pk_add_f32 v[74:75], v[72:73], -1.0 op_sel_hi:[1,0]
	v_lshlrev_b32_e32 v64, 16, v65
	v_pk_fma_f32 v[74:75], v[36:37], v[74:75], 1.0 op_sel_hi:[1,1,0]
	v_and_b32_e32 v65, 0xffff0000, v65
	v_pk_mul_f32 v[70:71], v[74:75], v[70:71]
	v_pk_mul_f32 v[74:75], v[58:59], v[72:73]
	v_pk_add_f32 v[72:73], v[64:65], -1.0 op_sel_hi:[1,0]
	v_pk_mul_f32 v[76:77], v[60:61], v[64:65]
	v_pk_fma_f32 v[72:73], v[38:39], v[72:73], 1.0 op_sel_hi:[1,1,0]
	v_xor_b32_e32 v65, 0x80000000, v59
	v_pk_mul_f32 v[72:73], v[72:73], v[66:67]
	v_xor_b32_e32 v67, 0x80000000, v61
	v_xor_b32_e32 v66, 0x80000000, v60
	v_xor_b32_e32 v64, 0x80000000, v58
	ds_write_b128 v68, v[64:67] offset:16
	ds_write_b128 v68, v[74:77] offset:32
	ds_write_b128 v68, v[70:73] offset:48
	v_lshlrev_b32_e32 v64, 16, v62
	v_and_b32_e32 v65, 0xffff0000, v62
	v_lshlrev_b32_e32 v62, 16, v63
	v_and_b32_e32 v63, 0xffff0000, v63
	v_mov_b32_e32 v66, v74
	v_mov_b32_e32 v67, v76
	v_mov_b32_e32 v76, v75
	v_mov_b32_e32 v74, v65
	v_mov_b32_e32 v75, v63
	v_mov_b32_e32 v78, v64
	v_mov_b32_e32 v79, v62
	v_pk_mul_f32 v[74:75], v[76:77], v[74:75]
	v_pk_mul_f32 v[70:71], v[70:71], v[64:65]
	v_pk_mul_f32 v[72:73], v[72:73], v[62:63]
	v_pk_fma_f32 v[66:67], v[66:67], v[78:79], v[74:75]
	v_add_f32_e32 v69, v70, v71
	v_add_f32_e32 v66, v66, v67
	v_add_f32_e32 v67, v72, v73
	v_add_f32_e32 v67, v69, v67
	v_add_f32_dpp v66, v66, v66 quad_perm:[1,0,3,2] row_mask:0xf bank_mask:0xf bound_ctrl:1
	s_nop 0
	v_add_f32_dpp v67, v67, v67 quad_perm:[1,0,3,2] row_mask:0xf bank_mask:0xf bound_ctrl:1
	v_add_f32_dpp v66, v66, v66 quad_perm:[2,3,0,1] row_mask:0xf bank_mask:0xf bound_ctrl:1
	s_nop 0
	v_add_f32_dpp v67, v67, v67 quad_perm:[2,3,0,1] row_mask:0xf bank_mask:0xf bound_ctrl:1
	v_add_f32_dpp v66, v66, v66 row_half_mirror row_mask:0xf bank_mask:0xf bound_ctrl:1
	s_nop 0
	v_add_f32_dpp v67, v67, v67 row_half_mirror row_mask:0xf bank_mask:0xf bound_ctrl:1
	v_add_f32_dpp v66, v66, v66 row_mirror row_mask:0xf bank_mask:0xf bound_ctrl:1
	v_pk_mul_f32 v[58:59], v[58:59], v[66:67] op_sel_hi:[1,0]
	v_pk_mul_f32 v[60:61], v[60:61], v[66:67] op_sel_hi:[1,0]
	v_mov_b32_dpp v69, v67 row_mirror row_mask:0xf bank_mask:0xf bound_ctrl:1
	v_pk_fma_f32 v[46:47], v[46:47], v[62:63], v[60:61] neg_lo:[0,0,1] neg_hi:[0,0,1]
	v_pk_fma_f32 v[44:45], v[44:45], v[64:65], v[58:59] neg_lo:[0,0,1] neg_hi:[0,0,1]
	ds_write_b128 v68, v[44:47] offset:64
	s_and_saveexec_b64 s[10:11], s[6:7]
	s_cbranch_execz .LBB0_447
	v_add_f32_e32 v61, v67, v69
	v_lshlrev_b32_e32 v44, 16, v54
	v_and_b32_e32 v45, 0xffff0000, v54
	v_lshlrev_b32_e32 v58, 16, v55
	v_and_b32_e32 v59, 0xffff0000, v55
	v_mul_f32_e32 v46, v61, v44
	v_mul_f32_e32 v47, v61, v45
	v_mul_f32_e32 v60, v61, v58
	v_mul_f32_e32 v61, v61, v59
	ds_write_b128 v153, v[44:47] offset:40960
	ds_write_b128 v153, v[58:61] offset:40976
.LBB0_447:
	s_or_b64 exec, exec, s[10:11]
	v_lshlrev_b32_e32 v44, 16, v56
	v_and_b32_e32 v45, 0xffff0000, v56
	v_lshlrev_b32_e32 v56, 16, v57
	v_and_b32_e32 v57, 0xffff0000, v57
	v_pk_mul_f32 v[46:47], v[32:33], v[44:45]
	v_pk_mul_f32 v[54:55], v[34:35], v[56:57]
	v_mov_b32_e32 v60, v47
	v_mov_b32_e32 v61, v55
	v_mov_b32_e32 v58, v46
	v_mov_b32_e32 v59, v54
	v_pk_mul_f32 v[60:61], v[60:61], v[60:61]
	s_mov_b32 s10, 0xf800000
	v_pk_fma_f32 v[58:59], v[58:59], v[58:59], v[60:61]
	v_add_u32_e32 v66, 0, v154
	v_add_f32_e32 v58, v58, v59
	s_waitcnt vmcnt(0) lgkmcnt(0)
	ds_write_b128 v66, v[40:43]
	v_add_f32_dpp v58, v58, v58 quad_perm:[1,0,3,2] row_mask:0xf bank_mask:0xf bound_ctrl:1
	s_nop 1
	v_add_f32_dpp v58, v58, v58 quad_perm:[2,3,0,1] row_mask:0xf bank_mask:0xf bound_ctrl:1
	s_nop 1
	v_add_f32_dpp v58, v58, v58 row_half_mirror row_mask:0xf bank_mask:0xf bound_ctrl:1
	s_nop 1
	v_add_f32_dpp v58, v58, v58 row_mirror row_mask:0xf bank_mask:0xf bound_ctrl:1
	v_mul_f32_e32 v59, 0x4f800000, v58
	v_cmp_gt_f32_e32 vcc, s10, v58
	s_nop 1
	v_cndmask_b32_e32 v58, v58, v59, vcc
	v_sqrt_f32_e32 v59, v58
	s_nop 0
	v_add_u32_e32 v60, -1, v59
	v_fma_f32 v61, -v60, v59, v58
	v_cmp_ge_f32_e64 s[10:11], 0, v61
	v_add_u32_e32 v61, 1, v59
	s_nop 0
	v_cndmask_b32_e64 v60, v59, v60, s[10:11]
	v_fma_f32 v59, -v61, v59, v58
	v_cmp_lt_f32_e64 s[10:11], 0, v59
	s_nop 1
	v_cndmask_b32_e64 v59, v60, v61, s[10:11]
	v_mul_f32_e32 v60, 0x37800000, v59
	v_cndmask_b32_e32 v59, v59, v60, vcc
	v_cmp_class_f32_e32 vcc, v58, v181
	s_nop 1
	v_cndmask_b32_e32 v58, v59, v58, vcc
	v_max_f32_e32 v58, 0x2b8cbccc, v58
	v_div_scale_f32 v59, s[10:11], v58, v58, 1.0
	v_rcp_f32_e32 v60, v59
	s_nop 0
	v_fma_f32 v61, -v59, v60, 1.0
	v_fmac_f32_e32 v60, v61, v60
	v_div_scale_f32 v61, vcc, 1.0, v58, 1.0
	v_mul_f32_e32 v62, v61, v60
	v_fma_f32 v63, -v59, v62, v61
	v_fmac_f32_e32 v62, v63, v60
	v_fma_f32 v59, -v59, v62, v61
	v_div_fmas_f32 v59, v59, v60, v62
	v_div_fixup_f32 v58, v59, v58, 1.0
	v_pk_mul_f32 v[62:63], v[46:47], v[58:59] op_sel_hi:[1,0]
	v_lshlrev_b32_e32 v46, 16, v52
	v_and_b32_e32 v47, 0xffff0000, v52
	v_pk_mul_f32 v[64:65], v[54:55], v[58:59] op_sel_hi:[1,0]
	v_pk_add_f32 v[54:55], v[46:47], -1.0 op_sel_hi:[1,0]
	v_lshlrev_b32_e32 v52, 16, v53
	v_pk_fma_f32 v[54:55], v[36:37], v[54:55], 1.0 op_sel_hi:[1,1,0]
	v_and_b32_e32 v53, 0xffff0000, v53
	v_pk_mul_f32 v[44:45], v[54:55], v[44:45]
	v_pk_mul_f32 v[54:55], v[62:63], v[46:47]
	v_pk_add_f32 v[46:47], v[52:53], -1.0 op_sel_hi:[1,0]
	v_xor_b32_e32 v61, 0x80000000, v65
	v_pk_fma_f32 v[46:47], v[38:39], v[46:47], 1.0 op_sel_hi:[1,1,0]
	v_xor_b32_e32 v60, 0x80000000, v64
	v_pk_mul_f32 v[46:47], v[46:47], v[56:57]
	v_pk_mul_f32 v[56:57], v[64:65], v[52:53]
	v_xor_b32_e32 v59, 0x80000000, v63
	v_xor_b32_e32 v58, 0x80000000, v62
	v_lshlrev_b32_e32 v52, 16, v50
	v_and_b32_e32 v53, 0xffff0000, v50
	v_lshlrev_b32_e32 v50, 16, v51
	v_and_b32_e32 v51, 0xffff0000, v51
	ds_write_b128 v66, v[58:61] offset:16
	ds_write_b128 v66, v[54:57] offset:32
	ds_write_b128 v66, v[44:47] offset:48
	v_mov_b32_e32 v58, v54
	v_mov_b32_e32 v59, v56
	v_mov_b32_e32 v56, v55
	v_mov_b32_e32 v54, v53
	v_mov_b32_e32 v55, v51
	v_mov_b32_e32 v60, v52
	v_mov_b32_e32 v61, v50
	v_pk_mul_f32 v[54:55], v[56:57], v[54:55]
	v_pk_mul_f32 v[44:45], v[44:45], v[52:53]
	v_pk_fma_f32 v[54:55], v[58:59], v[60:61], v[54:55]
	v_pk_mul_f32 v[46:47], v[46:47], v[50:51]
	v_add_f32_e32 v54, v54, v55
	v_add_f32_e32 v46, v46, v47
	v_add_f32_e32 v44, v44, v45
	v_add_f32_dpp v54, v54, v54 quad_perm:[1,0,3,2] row_mask:0xf bank_mask:0xf bound_ctrl:1
	v_add_f32_e32 v44, v44, v46
	s_nop 0
	v_add_f32_dpp v54, v54, v54 quad_perm:[2,3,0,1] row_mask:0xf bank_mask:0xf bound_ctrl:1
	v_add_f32_dpp v44, v44, v44 quad_perm:[1,0,3,2] row_mask:0xf bank_mask:0xf bound_ctrl:1
	s_nop 0
	v_add_f32_dpp v54, v54, v54 row_half_mirror row_mask:0xf bank_mask:0xf bound_ctrl:1
	v_add_f32_dpp v44, v44, v44 quad_perm:[2,3,0,1] row_mask:0xf bank_mask:0xf bound_ctrl:1
	s_nop 0
	v_add_f32_dpp v54, v54, v54 row_mirror row_mask:0xf bank_mask:0xf bound_ctrl:1
	v_add_f32_dpp v44, v44, v44 row_half_mirror row_mask:0xf bank_mask:0xf bound_ctrl:1
	v_pk_mul_f32 v[46:47], v[62:63], v[54:55] op_sel_hi:[1,0]
	v_pk_mul_f32 v[54:55], v[64:65], v[54:55] op_sel_hi:[1,0]
	v_mov_b32_dpp v45, v44 row_mirror row_mask:0xf bank_mask:0xf bound_ctrl:1
	v_pk_fma_f32 v[42:43], v[42:43], v[50:51], v[54:55] neg_lo:[0,0,1] neg_hi:[0,0,1]
	v_pk_fma_f32 v[40:41], v[40:41], v[52:53], v[46:47] neg_lo:[0,0,1] neg_hi:[0,0,1]
	ds_write_b128 v66, v[40:43] offset:64
	s_and_saveexec_b64 s[10:11], s[6:7]
	s_cbranch_execz .LBB0_449
	v_add_f32_e32 v47, v44, v45
	v_lshlrev_b32_e32 v40, 16, v48
	v_and_b32_e32 v41, 0xffff0000, v48
	v_lshlrev_b32_e32 v44, 16, v49
	v_and_b32_e32 v45, 0xffff0000, v49
	v_mul_f32_e32 v42, v47, v40
	v_mul_f32_e32 v43, v47, v41
	v_mul_f32_e32 v46, v47, v44
	v_mul_f32_e32 v47, v47, v45
	ds_write_b128 v156, v[40:43] offset:40960
	ds_write_b128 v156, v[44:47] offset:40976

; #define SC_GET(X, t) do { const float* p = rec + (t) * 320; w##X = *(const f32x4*)p; a##X = *(const f32x4*)(p + 4); b##X = *(const f32x4*)(p + 8); k##X = *(const f32x4*)(p + 12); q##X = *(const f32x4*)(p + 16); \
;                 v##X = *(const f32x4*)(VVa + (t) * 64); } while (0)
; DI void scan_phase(unsigned char* lds, const Ctx& a, const Op& d, const int variant) {
;     ...
;                 SC_GET(A, 0);
; #pragma unroll 2
;                 for (int t = 0; t < SC_T; t += 2) {
;                     SC_GET(B, t + 1);
;                     SC_STEP(A, t);
;                     if (t + 2 < SC_T) SC_GET(A, t + 2);
;                     SC_STEP(B, t + 1);
;                 }
.Lscan_steps:
	s_waitcnt lgkmcnt(1)
	v_pk_mul_f32 v[106:107], v[64:65], v[44:45] op_sel_hi:[1,0]
	ds_read_b128 v[72:75], v175 offset:1280
	v_pk_mul_f32 v[108:109], v[64:65], v[56:57] op_sel_hi:[1,0]
	ds_read_b128 v[76:79], v175 offset:1296
	v_pk_fma_f32 v[106:107], v[66:67], v[44:45], v[106:107] op_sel:[0,1,0]
	ds_read_b128 v[80:83], v175 offset:1312
	v_pk_fma_f32 v[108:109], v[66:67], v[56:57], v[108:109] op_sel:[0,1,0]
	ds_read_b128 v[84:87], v175 offset:1328
	v_pk_fma_f32 v[106:107], v[68:69], v[46:47], v[106:107] op_sel_hi:[1,0,1]
	ds_read_b128 v[88:91], v175 offset:1344
	v_pk_fma_f32 v[108:109], v[68:69], v[58:59], v[108:109] op_sel_hi:[1,0,1]
	ds_read_b128 v[92:95], v123 offset:41216
	v_pk_fma_f32 v[106:107], v[70:71], v[46:47], v[106:107] op_sel:[0,1,0]
	v_pk_fma_f32 v[108:109], v[70:71], v[58:59], v[108:109] op_sel:[0,1,0]
	v_pk_mul_f32 v[110:111], v[64:65], v[40:41] op_sel_hi:[1,0]
	v_add_f32_dpp v106, v106, v106 quad_perm:[1,0,3,2] row_mask:0xf bank_mask:0xf bound_ctrl:1
	v_add_f32_dpp v107, v107, v107 quad_perm:[1,0,3,2] row_mask:0xf bank_mask:0xf bound_ctrl:1
	v_pk_fma_f32 v[108:109], v[62:63], v[176:177], v[108:109]
	v_pk_mul_f32 v[112:113], v[66:67], v[40:41] op_sel:[0,1]
	v_add_f32_dpp v106, v106, v106 quad_perm:[2,3,0,1] row_mask:0xf bank_mask:0xf bound_ctrl:1
	v_add_f32_dpp v107, v107, v107 quad_perm:[2,3,0,1] row_mask:0xf bank_mask:0xf bound_ctrl:1
	v_add_f32_dpp v148, v108, v108 row_half_mirror row_mask:0xf bank_mask:0xf bound_ctrl:1
	v_add_f32_dpp v148, v109, v109 row_half_mirror row_mask:0xf bank_mask:0xa
	v_add_f32_dpp v106, v106, v106 row_half_mirror row_mask:0xf bank_mask:0xf bound_ctrl:1
	v_add_f32_dpp v107, v107, v107 row_half_mirror row_mask:0xf bank_mask:0xf bound_ctrl:1
	v_pk_mul_f32 v[144:145], v[68:69], v[42:43] op_sel_hi:[1,0]
	v_pk_mul_f32 v[146:147], v[70:71], v[42:43] op_sel:[0,1]
	v_add_f32_dpp v106, v106, v106 row_mirror row_mask:0xf bank_mask:0xf bound_ctrl:1
	v_add_f32_dpp v107, v107, v107 row_mirror row_mask:0xf bank_mask:0xf bound_ctrl:1
	v_pk_fma_f32 v[110:111], v[60:61], v[52:53], v[110:111] op_sel_hi:[1,0,1]
	v_pk_fma_f32 v[112:113], v[60:61], v[52:53], v[112:113] op_sel:[0,1,0]
	v_pk_fma_f32 v[144:145], v[60:61], v[54:55], v[144:145] op_sel_hi:[1,0,1]
	v_pk_fma_f32 v[146:147], v[60:61], v[54:55], v[146:147] op_sel:[0,1,0]
	v_pk_fma_f32 v[64:65], v[106:107], v[48:49], v[110:111] op_sel_hi:[1,0,1]
	v_pk_fma_f32 v[66:67], v[106:107], v[48:49], v[112:113] op_sel:[0,1,0]
	v_pk_fma_f32 v[68:69], v[106:107], v[50:51], v[144:145] op_sel_hi:[1,0,1]
	v_pk_fma_f32 v[70:71], v[106:107], v[50:51], v[146:147] op_sel:[0,1,0]
	s_waitcnt lgkmcnt(0)
	v_pk_mul_f32 v[106:107], v[64:65], v[76:77] op_sel_hi:[1,0]
	ds_read_b128 v[40:43], v175 offset:2560
	v_pk_mul_f32 v[108:109], v[64:65], v[88:89] op_sel_hi:[1,0]
	ds_read_b128 v[44:47], v175 offset:2576
	v_pk_fma_f32 v[106:107], v[66:67], v[76:77], v[106:107] op_sel:[0,1,0]
	ds_read_b128 v[48:51], v175 offset:2592
	v_pk_fma_f32 v[108:109], v[66:67], v[88:89], v[108:109] op_sel:[0,1,0]
	ds_read_b128 v[52:55], v175 offset:2608
	v_pk_fma_f32 v[106:107], v[68:69], v[78:79], v[106:107] op_sel_hi:[1,0,1]
	ds_read_b128 v[56:59], v175 offset:2624
	v_pk_fma_f32 v[108:109], v[68:69], v[90:91], v[108:109] op_sel_hi:[1,0,1]
	ds_read_b128 v[60:63], v123 offset:41472
	v_pk_fma_f32 v[106:107], v[70:71], v[78:79], v[106:107] op_sel:[0,1,0]
	v_pk_fma_f32 v[108:109], v[70:71], v[90:91], v[108:109] op_sel:[0,1,0]
	v_pk_mul_f32 v[110:111], v[64:65], v[72:73] op_sel_hi:[1,0]
	v_add_f32_dpp v106, v106, v106 quad_perm:[1,0,3,2] row_mask:0xf bank_mask:0xf bound_ctrl:1
	v_add_f32_dpp v107, v107, v107 quad_perm:[1,0,3,2] row_mask:0xf bank_mask:0xf bound_ctrl:1
	v_pk_fma_f32 v[108:109], v[94:95], v[176:177], v[108:109]
	v_pk_mul_f32 v[112:113], v[66:67], v[72:73] op_sel:[0,1]
	v_add_f32_dpp v106, v106, v106 quad_perm:[2,3,0,1] row_mask:0xf bank_mask:0xf bound_ctrl:1
	v_add_f32_dpp v107, v107, v107 quad_perm:[2,3,0,1] row_mask:0xf bank_mask:0xf bound_ctrl:1
	v_add_f32_dpp v149, v108, v108 row_half_mirror row_mask:0xf bank_mask:0xf bound_ctrl:1
	v_add_f32_dpp v149, v109, v109 row_half_mirror row_mask:0xf bank_mask:0xa
	v_add_f32_dpp v106, v106, v106 row_half_mirror row_mask:0xf bank_mask:0xf bound_ctrl:1
	v_add_f32_dpp v107, v107, v107 row_half_mirror row_mask:0xf bank_mask:0xf bound_ctrl:1
	v_pk_mul_f32 v[144:145], v[68:69], v[74:75] op_sel_hi:[1,0]
	v_pk_mul_f32 v[146:147], v[70:71], v[74:75] op_sel:[0,1]
	v_add_f32_dpp v150, v148, v148 row_ror:8 row_mask:0xf bank_mask:0xf bound_ctrl:1
	v_add_f32_dpp v150, v149, v149 row_ror:8 row_mask:0xf bank_mask:0xc
	v_add_f32_dpp v106, v106, v106 row_mirror row_mask:0xf bank_mask:0xf bound_ctrl:1
	v_add_f32_dpp v107, v107, v107 row_mirror row_mask:0xf bank_mask:0xf bound_ctrl:1
	v_pk_fma_f32 v[110:111], v[92:93], v[84:85], v[110:111] op_sel_hi:[1,0,1]
	v_pk_fma_f32 v[112:113], v[92:93], v[84:85], v[112:113] op_sel:[0,1,0]
	v_pk_fma_f32 v[144:145], v[92:93], v[86:87], v[144:145] op_sel_hi:[1,0,1]
	v_pk_fma_f32 v[146:147], v[92:93], v[86:87], v[146:147] op_sel:[0,1,0]
	v_add_f32_dpp v150, v150, v150 quad_perm:[1,0,3,2] row_mask:0xf bank_mask:0xf bound_ctrl:1
	v_pk_fma_f32 v[64:65], v[106:107], v[80:81], v[110:111] op_sel_hi:[1,0,1]
	v_pk_fma_f32 v[66:67], v[106:107], v[80:81], v[112:113] op_sel:[0,1,0]
	v_add_f32_dpp v150, v150, v150 quad_perm:[2,3,0,1] row_mask:0xf bank_mask:0xf bound_ctrl:1
	v_pk_fma_f32 v[68:69], v[106:107], v[82:83], v[144:145] op_sel_hi:[1,0,1]
	v_pk_fma_f32 v[70:71], v[106:107], v[82:83], v[146:147] op_sel:[0,1,0]
	s_mov_b64 exec, s[34:35]
	ds_write_b32 v178, v150 offset:0
	s_mov_b64 exec, -1
	s_waitcnt lgkmcnt(1)
; #define SC_GET(X, t) do { const float* p = rec + (t) * 320; w##X = *(const f32x4*)p; a##X = *(const f32x4*)(p + 4); b##X = *(const f32x4*)(p + 8); k##X = *(const f32x4*)(p + 12); q##X = *(const f32x4*)(p + 16); \
;                 v##X = *(const f32x4*)(VVa + (t) * 64); } while (0)
; DI void scan_phase(unsigned char* lds, const Ctx& a, const Op& d, const int variant) {
;     ...
;                 SC_GET(A, 0);
; #pragma unroll 2
;                 for (int t = 0; t < SC_T; t += 2) {
;                     SC_GET(B, t + 1);
;                     SC_STEP(A, t);
;                     if (t + 2 < SC_T) SC_GET(A, t + 2);
;                     SC_STEP(B, t + 1);
;                 }
	v_pk_mul_f32 v[106:107], v[64:65], v[44:45] op_sel_hi:[1,0]
	ds_read_b128 v[72:75], v175 offset:3840
	v_pk_mul_f32 v[108:109], v[64:65], v[56:57] op_sel_hi:[1,0]
	ds_read_b128 v[76:79], v175 offset:3856
	v_pk_fma_f32 v[106:107], v[66:67], v[44:45], v[106:107] op_sel:[0,1,0]
	ds_read_b128 v[80:83], v175 offset:3872
	v_pk_fma_f32 v[108:109], v[66:67], v[56:57], v[108:109] op_sel:[0,1,0]
	ds_read_b128 v[84:87], v175 offset:3888
	v_pk_fma_f32 v[106:107], v[68:69], v[46:47], v[106:107] op_sel_hi:[1,0,1]
	ds_read_b128 v[88:91], v175 offset:3904
	v_pk_fma_f32 v[108:109], v[68:69], v[58:59], v[108:109] op_sel_hi:[1,0,1]
	ds_read_b128 v[92:95], v123 offset:41728
	v_pk_fma_f32 v[106:107], v[70:71], v[46:47], v[106:107] op_sel:[0,1,0]
	v_pk_fma_f32 v[108:109], v[70:71], v[58:59], v[108:109] op_sel:[0,1,0]
	v_pk_mul_f32 v[110:111], v[64:65], v[40:41] op_sel_hi:[1,0]
	v_add_f32_dpp v106, v106, v106 quad_perm:[1,0,3,2] row_mask:0xf bank_mask:0xf bound_ctrl:1
	v_add_f32_dpp v107, v107, v107 quad_perm:[1,0,3,2] row_mask:0xf bank_mask:0xf bound_ctrl:1
	v_pk_fma_f32 v[108:109], v[62:63], v[176:177], v[108:109]
	v_pk_mul_f32 v[112:113], v[66:67], v[40:41] op_sel:[0,1]
	v_add_f32_dpp v106, v106, v106 quad_perm:[2,3,0,1] row_mask:0xf bank_mask:0xf bound_ctrl:1
	v_add_f32_dpp v107, v107, v107 quad_perm:[2,3,0,1] row_mask:0xf bank_mask:0xf bound_ctrl:1
	v_add_f32_dpp v148, v108, v108 row_half_mirror row_mask:0xf bank_mask:0xf bound_ctrl:1
	v_add_f32_dpp v148, v109, v109 row_half_mirror row_mask:0xf bank_mask:0xa
	v_add_f32_dpp v106, v106, v106 row_half_mirror row_mask:0xf bank_mask:0xf bound_ctrl:1
	v_add_f32_dpp v107, v107, v107 row_half_mirror row_mask:0xf bank_mask:0xf bound_ctrl:1
	v_pk_mul_f32 v[144:145], v[68:69], v[42:43] op_sel_hi:[1,0]
	v_pk_mul_f32 v[146:147], v[70:71], v[42:43] op_sel:[0,1]
	v_add_f32_dpp v106, v106, v106 row_mirror row_mask:0xf bank_mask:0xf bound_ctrl:1
	v_add_f32_dpp v107, v107, v107 row_mirror row_mask:0xf bank_mask:0xf bound_ctrl:1
	v_pk_fma_f32 v[110:111], v[60:61], v[52:53], v[110:111] op_sel_hi:[1,0,1]
	v_pk_fma_f32 v[112:113], v[60:61], v[52:53], v[112:113] op_sel:[0,1,0]
	v_pk_fma_f32 v[144:145], v[60:61], v[54:55], v[144:145] op_sel_hi:[1,0,1]
	v_pk_fma_f32 v[146:147], v[60:61], v[54:55], v[146:147] op_sel:[0,1,0]
	v_pk_fma_f32 v[64:65], v[106:107], v[48:49], v[110:111] op_sel_hi:[1,0,1]
	v_pk_fma_f32 v[66:67], v[106:107], v[48:49], v[112:113] op_sel:[0,1,0]
	v_pk_fma_f32 v[68:69], v[106:107], v[50:51], v[144:145] op_sel_hi:[1,0,1]
	v_pk_fma_f32 v[70:71], v[106:107], v[50:51], v[146:147] op_sel:[0,1,0]
	s_waitcnt lgkmcnt(0)
	v_pk_mul_f32 v[106:107], v[64:65], v[76:77] op_sel_hi:[1,0]
	ds_read_b128 v[40:43], v175 offset:5120
	v_pk_mul_f32 v[108:109], v[64:65], v[88:89] op_sel_hi:[1,0]
	ds_read_b128 v[44:47], v175 offset:5136
	v_pk_fma_f32 v[106:107], v[66:67], v[76:77], v[106:107] op_sel:[0,1,0]
	ds_read_b128 v[48:51], v175 offset:5152
	v_pk_fma_f32 v[108:109], v[66:67], v[88:89], v[108:109] op_sel:[0,1,0]
	ds_read_b128 v[52:55], v175 offset:5168
	v_pk_fma_f32 v[106:107], v[68:69], v[78:79], v[106:107] op_sel_hi:[1,0,1]
	ds_read_b128 v[56:59], v175 offset:5184
	v_pk_fma_f32 v[108:109], v[68:69], v[90:91], v[108:109] op_sel_hi:[1,0,1]
	ds_read_b128 v[60:63], v123 offset:41984
	v_pk_fma_f32 v[106:107], v[70:71], v[78:79], v[106:107] op_sel:[0,1,0]
	v_pk_fma_f32 v[108:109], v[70:71], v[90:91], v[108:109] op_sel:[0,1,0]
	v_pk_mul_f32 v[110:111], v[64:65], v[72:73] op_sel_hi:[1,0]
	v_add_f32_dpp v106, v106, v106 quad_perm:[1,0,3,2] row_mask:0xf bank_mask:0xf bound_ctrl:1
	v_add_f32_dpp v107, v107, v107 quad_perm:[1,0,3,2] row_mask:0xf bank_mask:0xf bound_ctrl:1
	v_pk_fma_f32 v[108:109], v[94:95], v[176:177], v[108:109]
	v_pk_mul_f32 v[112:113], v[66:67], v[72:73] op_sel:[0,1]
	v_add_f32_dpp v106, v106, v106 quad_perm:[2,3,0,1] row_mask:0xf bank_mask:0xf bound_ctrl:1
	v_add_f32_dpp v107, v107, v107 quad_perm:[2,3,0,1] row_mask:0xf bank_mask:0xf bound_ctrl:1
	v_add_f32_dpp v149, v108, v108 row_half_mirror row_mask:0xf bank_mask:0xf bound_ctrl:1
	v_add_f32_dpp v149, v109, v109 row_half_mirror row_mask:0xf bank_mask:0xa
	v_add_f32_dpp v106, v106, v106 row_half_mirror row_mask:0xf bank_mask:0xf bound_ctrl:1
	v_add_f32_dpp v107, v107, v107 row_half_mirror row_mask:0xf bank_mask:0xf bound_ctrl:1
	v_pk_mul_f32 v[144:145], v[68:69], v[74:75] op_sel_hi:[1,0]
	v_pk_mul_f32 v[146:147], v[70:71], v[74:75] op_sel:[0,1]
	v_add_f32_dpp v150, v148, v148 row_ror:8 row_mask:0xf bank_mask:0xf bound_ctrl:1
	v_add_f32_dpp v150, v149, v149 row_ror:8 row_mask:0xf bank_mask:0xc
	v_add_f32_dpp v106, v106, v106 row_mirror row_mask:0xf bank_mask:0xf bound_ctrl:1
	v_add_f32_dpp v107, v107, v107 row_mirror row_mask:0xf bank_mask:0xf bound_ctrl:1
	v_pk_fma_f32 v[110:111], v[92:93], v[84:85], v[110:111] op_sel_hi:[1,0,1]
	v_pk_fma_f32 v[112:113], v[92:93], v[84:85], v[112:113] op_sel:[0,1,0]
	v_pk_fma_f32 v[144:145], v[92:93], v[86:87], v[144:145] op_sel_hi:[1,0,1]
	v_pk_fma_f32 v[146:147], v[92:93], v[86:87], v[146:147] op_sel:[0,1,0]
	v_add_f32_dpp v150, v150, v150 quad_perm:[1,0,3,2] row_mask:0xf bank_mask:0xf bound_ctrl:1
	v_pk_fma_f32 v[64:65], v[106:107], v[80:81], v[110:111] op_sel_hi:[1,0,1]
	v_pk_fma_f32 v[66:67], v[106:107], v[80:81], v[112:113] op_sel:[0,1,0]
	v_add_f32_dpp v150, v150, v150 quad_perm:[2,3,0,1] row_mask:0xf bank_mask:0xf bound_ctrl:1
	v_pk_fma_f32 v[68:69], v[106:107], v[82:83], v[144:145] op_sel_hi:[1,0,1]
	v_pk_fma_f32 v[70:71], v[106:107], v[82:83], v[146:147] op_sel:[0,1,0]
	s_mov_b64 exec, s[34:35]
	ds_write_b32 v178, v150 offset:256
	s_mov_b64 exec, -1
	v_add_u32_e32 v175, 0x1400, v175
	v_add_u32_e32 v123, 0x400, v123
	v_add_u32_e32 v178, 0x200, v178
	s_add_i32 s38, s38, -1
	s_cmp_lg_u32 s38, 0
	s_cbranch_scc1 .Lscan_steps
	s_setprio 0

; #define SC_STORE2(bi) do { SC_STORE(bi, tl0, pr, pk, pv, pa, pd); SC_STORE(bi, tl0 + 16, pr2, pk2_, pv2, pa2, pd2); } while (0)
; DI void scan_phase(unsigned char* lds, const Ctx& a, const Op& d, const int variant) {
;     ...
;                 if (c + 1 < NCH) SC_STORE2(bi ^ 1);
.LBB0_483:
	s_waitcnt vmcnt(0)
	v_lshlrev_b32_e32 v40, 16, v126
	v_and_b32_e32 v41, 0xffff0000, v126
	v_lshlrev_b32_e32 v46, 16, v127
	v_and_b32_e32 v47, 0xffff0000, v127
	v_pk_mul_f32 v[44:45], v[32:33], v[40:41]
	v_pk_mul_f32 v[48:49], v[34:35], v[46:47]
	v_mov_b32_e32 v52, v45
	v_mov_b32_e32 v53, v49
	v_mov_b32_e32 v50, v44
	v_mov_b32_e32 v51, v48
	v_pk_mul_f32 v[52:53], v[52:53], v[52:53]
	s_mov_b32 s10, 0xf800000
	v_pk_fma_f32 v[50:51], v[50:51], v[50:51], v[52:53]
	s_nop 0
	v_add_f32_e32 v43, v50, v51
	s_nop 1
	v_add_f32_dpp v43, v43, v43 quad_perm:[1,0,3,2] row_mask:0xf bank_mask:0xf bound_ctrl:1
	s_nop 1
	v_add_f32_dpp v43, v43, v43 quad_perm:[2,3,0,1] row_mask:0xf bank_mask:0xf bound_ctrl:1
	s_nop 1
	v_add_f32_dpp v43, v43, v43 row_half_mirror row_mask:0xf bank_mask:0xf bound_ctrl:1
	s_nop 1
	v_add_f32_dpp v43, v43, v43 row_mirror row_mask:0xf bank_mask:0xf bound_ctrl:1
	v_mul_f32_e32 v50, 0x4f800000, v43
	v_cmp_gt_f32_e32 vcc, s10, v43
	s_xor_b32 s10, s48, 1
	s_mul_i32 s34, s10, 0xd000
	v_cndmask_b32_e32 v43, v43, v50, vcc
	v_sqrt_f32_e32 v50, v43
	s_add_i32 s34, s34, 0
	v_add_u32_e32 v62, s34, v117
	ds_write_b128 v62, v[98:101]
	v_add_u32_e32 v51, -1, v50
	v_fma_f32 v52, -v51, v50, v43
	v_cmp_ge_f32_e64 s[10:11], 0, v52
	v_add_u32_e32 v52, 1, v50
	s_nop 0
	v_cndmask_b32_e64 v51, v50, v51, s[10:11]
	v_fma_f32 v50, -v52, v50, v43
	v_cmp_lt_f32_e64 s[10:11], 0, v50
	s_nop 1
	v_cndmask_b32_e64 v50, v51, v52, s[10:11]
	v_mul_f32_e32 v51, 0x37800000, v50
	v_cndmask_b32_e32 v50, v50, v51, vcc
	v_cmp_class_f32_e32 vcc, v43, v181
	s_nop 1
	v_cndmask_b32_e32 v43, v50, v43, vcc
	v_max_f32_e32 v43, 0x2b8cbccc, v43
	v_div_scale_f32 v50, s[10:11], v43, v43, 1.0
	v_rcp_f32_e32 v51, v50
	s_nop 0
	v_fma_f32 v52, -v50, v51, 1.0
	v_fmac_f32_e32 v51, v52, v51
	v_div_scale_f32 v52, vcc, 1.0, v43, 1.0
	v_mul_f32_e32 v53, v52, v51
	v_fma_f32 v54, -v50, v53, v52
	v_fmac_f32_e32 v53, v54, v51
	v_fma_f32 v50, -v50, v53, v52
	v_div_fmas_f32 v50, v50, v51, v53
	v_div_fixup_f32 v50, v50, v43, 1.0
	v_pk_mul_f32 v[58:59], v[48:49], v[50:51] op_sel_hi:[1,0]
	v_lshlrev_b32_e32 v48, 16, v130
	v_and_b32_e32 v49, 0xffff0000, v130
	v_pk_mul_f32 v[56:57], v[44:45], v[50:51] op_sel_hi:[1,0]
	v_pk_add_f32 v[44:45], v[48:49], -1.0 op_sel_hi:[1,0]
	v_xor_b32_e32 v55, 0x80000000, v59
	v_pk_fma_f32 v[44:45], v[36:37], v[44:45], 1.0 op_sel_hi:[1,1,0]
	v_xor_b32_e32 v54, 0x80000000, v58
	v_pk_mul_f32 v[44:45], v[44:45], v[40:41]
	v_lshlrev_b32_e32 v40, 16, v131
	v_and_b32_e32 v41, 0xffff0000, v131
	v_pk_add_f32 v[50:51], v[40:41], -1.0 op_sel_hi:[1,0]
	v_xor_b32_e32 v53, 0x80000000, v57
	v_pk_fma_f32 v[50:51], v[38:39], v[50:51], 1.0 op_sel_hi:[1,1,0]
	v_xor_b32_e32 v52, 0x80000000, v56
	v_pk_mul_f32 v[48:49], v[56:57], v[48:49]
	v_pk_mul_f32 v[46:47], v[50:51], v[46:47]
	v_pk_mul_f32 v[50:51], v[58:59], v[40:41]
	ds_write_b128 v62, v[52:55] offset:16
	ds_write_b128 v62, v[48:51] offset:32
	ds_write_b128 v62, v[44:47] offset:48
	v_lshlrev_b32_e32 v52, 16, v124
	v_and_b32_e32 v53, 0xffff0000, v124
	v_pk_mul_f32 v[40:41], v[44:45], v[52:53]
	v_and_b32_e32 v45, 0xffff0000, v125
	v_lshlrev_b32_e32 v44, 16, v125
	v_mov_b32_e32 v54, v48
	v_mov_b32_e32 v55, v50
	v_mov_b32_e32 v50, v49
	v_mov_b32_e32 v48, v53
	v_mov_b32_e32 v49, v45
	v_mov_b32_e32 v60, v52
	v_mov_b32_e32 v61, v44
	v_pk_mul_f32 v[48:49], v[50:51], v[48:49]
	v_pk_mul_f32 v[46:47], v[46:47], v[44:45]
	v_pk_fma_f32 v[48:49], v[54:55], v[60:61], v[48:49]
	v_add_f32_e32 v40, v40, v41
	v_add_f32_e32 v43, v48, v49
	s_nop 1
	v_add_f32_dpp v43, v43, v43 quad_perm:[1,0,3,2] row_mask:0xf bank_mask:0xf bound_ctrl:1
	s_nop 1
	v_add_f32_dpp v43, v43, v43 quad_perm:[2,3,0,1] row_mask:0xf bank_mask:0xf bound_ctrl:1
	s_nop 1
	v_add_f32_dpp v43, v43, v43 row_half_mirror row_mask:0xf bank_mask:0xf bound_ctrl:1
	s_nop 1
	v_add_f32_dpp v48, v43, v43 row_mirror row_mask:0xf bank_mask:0xf bound_ctrl:1
	v_add_f32_e32 v43, v46, v47
	v_add_f32_e32 v40, v40, v43
	v_pk_mul_f32 v[50:51], v[56:57], v[48:49] op_sel_hi:[1,0]
	v_pk_mul_f32 v[46:47], v[58:59], v[48:49] op_sel_hi:[1,0]
	v_add_f32_dpp v40, v40, v40 quad_perm:[1,0,3,2] row_mask:0xf bank_mask:0xf bound_ctrl:1
	v_pk_fma_f32 v[46:47], v[100:101], v[44:45], v[46:47] neg_lo:[0,0,1] neg_hi:[0,0,1]
	v_pk_fma_f32 v[44:45], v[98:99], v[52:53], v[50:51] neg_lo:[0,0,1] neg_hi:[0,0,1]
	v_add_f32_dpp v40, v40, v40 quad_perm:[2,3,0,1] row_mask:0xf bank_mask:0xf bound_ctrl:1
	ds_write_b128 v62, v[44:47] offset:64
	s_nop 0
	v_add_f32_dpp v40, v40, v40 row_half_mirror row_mask:0xf bank_mask:0xf bound_ctrl:1
	s_nop 1
	v_mov_b32_dpp v41, v40 row_mirror row_mask:0xf bank_mask:0xf bound_ctrl:1
	s_and_saveexec_b64 s[10:11], s[6:7]
	s_cbranch_execz .LBB0_485
	v_add_f32_e32 v40, v40, v41
	v_lshlrev_b32_e32 v44, 16, v128
	v_and_b32_e32 v45, 0xffff0000, v128
	v_lshlrev_b32_e32 v48, 16, v129
	v_and_b32_e32 v49, 0xffff0000, v129
	v_add3_u32 v41, s34, v121, v152
	v_mul_f32_e32 v46, v40, v44
	v_mul_f32_e32 v47, v40, v45
	v_mul_f32_e32 v50, v40, v48
	v_mul_f32_e32 v51, v40, v49
	ds_write_b128 v41, v[44:47] offset:40960
	ds_write_b128 v41, v[48:51] offset:40976
; #define SC_STORE2(bi) do { SC_STORE(bi, tl0, pr, pk, pv, pa, pd); SC_STORE(bi, tl0 + 16, pr2, pk2_, pv2, pa2, pd2); } while (0)
; DI void scan_phase(unsigned char* lds, const Ctx& a, const Op& d, const int variant) {
;     ...
;                 if (c + 1 < NCH) SC_STORE2(bi ^ 1);
.LBB0_485:
	s_or_b64 exec, exec, s[10:11]
	v_lshlrev_b32_e32 v40, 16, v134
	v_and_b32_e32 v41, 0xffff0000, v134
	v_lshlrev_b32_e32 v46, 16, v135
	v_and_b32_e32 v47, 0xffff0000, v135
	v_pk_mul_f32 v[44:45], v[32:33], v[40:41]
	v_pk_mul_f32 v[48:49], v[34:35], v[46:47]
	v_mov_b32_e32 v52, v45
	v_mov_b32_e32 v53, v49
	v_mov_b32_e32 v50, v44
	v_mov_b32_e32 v51, v48
	v_pk_mul_f32 v[52:53], v[52:53], v[52:53]
	s_mov_b32 s10, 0xf800000
	v_pk_fma_f32 v[50:51], v[50:51], v[50:51], v[52:53]
	v_add_u32_e32 v62, s34, v154
	v_add_f32_e32 v43, v50, v51
	ds_write_b128 v62, v[102:105]
	s_nop 0
	v_add_f32_dpp v43, v43, v43 quad_perm:[1,0,3,2] row_mask:0xf bank_mask:0xf bound_ctrl:1
	s_nop 1
	v_add_f32_dpp v43, v43, v43 quad_perm:[2,3,0,1] row_mask:0xf bank_mask:0xf bound_ctrl:1
	s_nop 1
	v_add_f32_dpp v43, v43, v43 row_half_mirror row_mask:0xf bank_mask:0xf bound_ctrl:1
	s_nop 1
	v_add_f32_dpp v43, v43, v43 row_mirror row_mask:0xf bank_mask:0xf bound_ctrl:1
	v_mul_f32_e32 v50, 0x4f800000, v43
	v_cmp_gt_f32_e32 vcc, s10, v43
	s_nop 1
	v_cndmask_b32_e32 v43, v43, v50, vcc
	v_sqrt_f32_e32 v50, v43
	s_nop 0
	v_add_u32_e32 v51, -1, v50
	v_fma_f32 v52, -v51, v50, v43
	v_cmp_ge_f32_e64 s[10:11], 0, v52
	v_add_u32_e32 v52, 1, v50
	s_nop 0
	v_cndmask_b32_e64 v51, v50, v51, s[10:11]
	v_fma_f32 v50, -v52, v50, v43
	v_cmp_lt_f32_e64 s[10:11], 0, v50
	s_nop 1
	v_cndmask_b32_e64 v50, v51, v52, s[10:11]
	v_mul_f32_e32 v51, 0x37800000, v50
	v_cndmask_b32_e32 v50, v50, v51, vcc
	v_cmp_class_f32_e32 vcc, v43, v181
	s_nop 1
	v_cndmask_b32_e32 v43, v50, v43, vcc
	v_max_f32_e32 v43, 0x2b8cbccc, v43
	v_div_scale_f32 v50, s[10:11], v43, v43, 1.0
	v_rcp_f32_e32 v51, v50
	s_nop 0
	v_fma_f32 v52, -v50, v51, 1.0
	v_fmac_f32_e32 v51, v52, v51
	v_div_scale_f32 v52, vcc, 1.0, v43, 1.0
	v_mul_f32_e32 v53, v52, v51
	v_fma_f32 v54, -v50, v53, v52
	v_fmac_f32_e32 v53, v54, v51
	v_fma_f32 v50, -v50, v53, v52
	v_div_fmas_f32 v50, v50, v51, v53
	v_div_fixup_f32 v50, v50, v43, 1.0
	v_pk_mul_f32 v[58:59], v[48:49], v[50:51] op_sel_hi:[1,0]
	v_lshlrev_b32_e32 v48, 16, v138
	v_and_b32_e32 v49, 0xffff0000, v138
	v_pk_mul_f32 v[56:57], v[44:45], v[50:51] op_sel_hi:[1,0]
	v_pk_add_f32 v[44:45], v[48:49], -1.0 op_sel_hi:[1,0]
	v_xor_b32_e32 v55, 0x80000000, v59
	v_pk_fma_f32 v[44:45], v[36:37], v[44:45], 1.0 op_sel_hi:[1,1,0]
	v_xor_b32_e32 v54, 0x80000000, v58
	v_pk_mul_f32 v[44:45], v[44:45], v[40:41]
	v_lshlrev_b32_e32 v40, 16, v139
	v_and_b32_e32 v41, 0xffff0000, v139
	v_pk_add_f32 v[50:51], v[40:41], -1.0 op_sel_hi:[1,0]
	v_xor_b32_e32 v53, 0x80000000, v57
	v_pk_fma_f32 v[50:51], v[38:39], v[50:51], 1.0 op_sel_hi:[1,1,0]
	v_xor_b32_e32 v52, 0x80000000, v56
	v_pk_mul_f32 v[48:49], v[56:57], v[48:49]
	v_pk_mul_f32 v[46:47], v[50:51], v[46:47]
	v_pk_mul_f32 v[50:51], v[58:59], v[40:41]
	ds_write_b128 v62, v[52:55] offset:16
	ds_write_b128 v62, v[48:51] offset:32
	ds_write_b128 v62, v[44:47] offset:48
	v_lshlrev_b32_e32 v52, 16, v132
	v_and_b32_e32 v53, 0xffff0000, v132
	v_pk_mul_f32 v[40:41], v[44:45], v[52:53]
	v_and_b32_e32 v45, 0xffff0000, v133
	v_lshlrev_b32_e32 v44, 16, v133
	v_mov_b32_e32 v54, v48
	v_mov_b32_e32 v55, v50
	v_mov_b32_e32 v50, v49
	v_mov_b32_e32 v48, v53
	v_mov_b32_e32 v49, v45
	v_mov_b32_e32 v60, v52
	v_mov_b32_e32 v61, v44
	v_pk_mul_f32 v[48:49], v[50:51], v[48:49]
	v_pk_mul_f32 v[46:47], v[46:47], v[44:45]
	v_pk_fma_f32 v[48:49], v[54:55], v[60:61], v[48:49]
	v_add_f32_e32 v40, v40, v41
	v_add_f32_e32 v43, v48, v49
	s_nop 1
	v_add_f32_dpp v43, v43, v43 quad_perm:[1,0,3,2] row_mask:0xf bank_mask:0xf bound_ctrl:1
	s_nop 1
	v_add_f32_dpp v43, v43, v43 quad_perm:[2,3,0,1] row_mask:0xf bank_mask:0xf bound_ctrl:1
	s_nop 1
	v_add_f32_dpp v43, v43, v43 row_half_mirror row_mask:0xf bank_mask:0xf bound_ctrl:1
	s_nop 1
	v_add_f32_dpp v48, v43, v43 row_mirror row_mask:0xf bank_mask:0xf bound_ctrl:1
	v_add_f32_e32 v43, v46, v47
	v_add_f32_e32 v40, v40, v43
	v_pk_mul_f32 v[50:51], v[56:57], v[48:49] op_sel_hi:[1,0]
	v_pk_mul_f32 v[46:47], v[58:59], v[48:49] op_sel_hi:[1,0]
	v_add_f32_dpp v40, v40, v40 quad_perm:[1,0,3,2] row_mask:0xf bank_mask:0xf bound_ctrl:1
	v_pk_fma_f32 v[46:47], v[104:105], v[44:45], v[46:47] neg_lo:[0,0,1] neg_hi:[0,0,1]
	v_pk_fma_f32 v[44:45], v[102:103], v[52:53], v[50:51] neg_lo:[0,0,1] neg_hi:[0,0,1]
	v_add_f32_dpp v40, v40, v40 quad_perm:[2,3,0,1] row_mask:0xf bank_mask:0xf bound_ctrl:1
	ds_write_b128 v62, v[44:47] offset:64
	s_nop 0
	v_add_f32_dpp v40, v40, v40 row_half_mirror row_mask:0xf bank_mask:0xf bound_ctrl:1
	s_nop 1
	v_mov_b32_dpp v41, v40 row_mirror row_mask:0xf bank_mask:0xf bound_ctrl:1
	s_and_saveexec_b64 s[10:11], s[6:7]
	s_cbranch_execz .LBB0_487
	v_add_f32_e32 v40, v40, v41
	v_lshlrev_b32_e32 v44, 16, v136
	v_and_b32_e32 v45, 0xffff0000, v136
	v_lshlrev_b32_e32 v48, 16, v137
	v_and_b32_e32 v49, 0xffff0000, v137
	v_add3_u32 v41, s34, v155, v152
	v_mul_f32_e32 v46, v40, v44
	v_mul_f32_e32 v47, v40, v45
	v_mul_f32_e32 v50, v40, v48
	v_mul_f32_e32 v51, v40, v49
	ds_write_b128 v41, v[44:47] offset:40960
	ds_write_b128 v41, v[48:51] offset:40976
